# prep pass 1: the row's pointer s_loads and its six global loads issued together, conversions and stores behind counted vmcnt waits (was four serial load-store round trips)
# speedup vs baseline: 1.0013x; 1.0013x over previous
.LBB0_903:
	v_mov_b32_e32 v20, v1
	v_lshl_add_u64 v[24:25], v[10:11], 0, v[12:13]
	v_mov_b32_e32 v21, v20
	v_ashrrev_i32_e32 v15, 7, v18
	global_store_dwordx2 v[24:25], v[20:21], off
	v_and_b32_e32 v15, -2, v15
	s_load_dwordx2 s[4:5], s[40:41], 0x10
	s_load_dwordx2 s[98:99], s[40:41], 0x18
	s_load_dwordx4 s[36:39], s[40:41], 0x20
	v_readlane_b32 s34, v254, 29
	s_movk_i32 s3, 0x7f80
	v_readlane_b32 s35, v254, 30
	v_add_u32_e32 v20, s34, v15
	v_ashrrev_i32_e32 v21, 31, v20
	v_lshlrev_b64 v[20:21], 15, v[20:21]
	v_and_or_b32 v20, v22, s3, v20
	v_lshlrev_b64 v[142:143], 2, v[20:21]
	s_waitcnt lgkmcnt(0)
	v_lshl_add_u64 v[24:25], v[20:21], 2, s[4:5]
	v_lshl_add_u64 v[24:25], v[24:25], 0, v[0:1]
	global_load_dwordx2 v[140:141], v[24:25], off
	v_lshl_add_u64 v[144:145], s[36:37], 0, v[142:143]
	v_lshl_add_u64 v[144:145], v[144:145], 0, v[0:1]
	global_load_dwordx2 v[146:147], v[144:145], off
	v_lshl_add_u64 v[144:145], s[38:39], 0, v[142:143]
	v_lshl_add_u64 v[144:145], v[144:145], 0, v[0:1]
	global_load_dwordx2 v[148:149], v[144:145], off
	s_and_saveexec_b64 s[4:5], vcc
	v_mov_b32_e32 v15, v1
	v_mov_b32_e32 v17, v1
	v_lshl_add_u64 v[24:25], s[98:99], 0, v[20:21]
	v_lshl_add_u64 v[24:25], v[24:25], 0, v[14:15]
	v_lshl_add_u64 v[24:25], v[24:25], 0, v[16:17]
	global_load_dword v150, v[24:25], off
	global_load_dword v151, v[24:25], off offset:32
	s_or_b64 exec, exec, s[4:5]
	s_waitcnt vmcnt(4)
	v_cvt_pk_bf16_f32 v15, v140, v141
	v_lshl_add_u64 v[24:25], v[10:11], 0, v[8:9]
	global_store_dword v[24:25], v15, off
	v_ashrrev_i32_e32 v19, 31, v18
	s_waitcnt vmcnt(4)
	v_cvt_pk_bf16_f32 v15, v146, v147
	v_lshlrev_b64 v[24:25], 8, v[18:19]
	v_lshl_add_u64 v[26:27], v[2:3], 0, v[24:25]
	global_store_dword v[26:27], v15, off
	s_waitcnt vmcnt(4)
	v_cvt_pk_bf16_f32 v15, v148, v149
	v_lshl_add_u64 v[20:21], v[4:5], 0, v[24:25]
	global_store_dword v[20:21], v15, off
	s_waitcnt vmcnt(3)
	s_and_saveexec_b64 s[4:5], vcc
	v_cvt_pk_bf16_f32 v15, v150, v151
	global_store_dword v[6:7], v15, off
	s_or_b64 exec, exec, s[4:5]
	v_add_u32_e32 v22, s2, v22
	v_lshl_add_u64 v[6:7], v[6:7], 0, s[26:27]
	v_lshl_add_u64 v[10:11], v[10:11], 0, s[28:29]
	s_movk_i32 s3, 0x67ff
	v_add_u32_e32 v18, s20, v18
	v_add_u32_e32 v15, 0x6000, v18
	v_cmp_lt_i32_e64 s[4:5], s3, v15
	s_or_b64 s[30:31], s[4:5], s[30:31]
	s_andn2_b64 exec, exec, s[30:31]
	s_cbranch_execz .LBB0_1143
	s_branch .LBB0_903
